# v20 + the grid barrier between mixer A and hgrn_m3 replaced by per-range flags (agent-scope stores/loads of the range summaries, workgroup-local sync kept)
# speedup vs baseline: 1.0004x; 1.0004x over previous
; __device__ __forceinline__ unsigned cvt_pk_bf16(float lo, float hi) { f32x2_t v = {lo, hi}; bf16x2_t b = __builtin_convertvector(v, bf16x2_t); return __builtin_bit_cast(unsigned, b); }
; __device__ __forceinline__ void hgrn_m1(Frame& F) {
;     ...
; #pragma unroll
;         for (int x = 0; x < 2; ++x)
; #pragma unroll
;             for (int g4 = 0; g4 < 4; ++g4) { u32x2 w; w.x = cvt_pk_bf16(st[x][4 * g4], st[x][4 * g4 + 1]); w.y = cvt_pk_bf16(st[x][4 * g4 + 2], st[x][4 * g4 + 3]);
;                 *(u32x2*)(RS + (size_t)rg * 16384 + (size_t)(32 * (vt0 + x) + r32) * 128 + 32 * kt + 8 * g4 + 4 * hi) = w; }
;         if (i == 0) RD[(size_t)rg * 128 + k] = dpre;
.LBB0_300:
	s_ashr_i32 s11, s10, 31
	s_lshl_b64 s[12:13], s[10:11], 15
	v_lshl_add_u64 v[44:45], v[38:39], 0, s[12:13]
	v_mov_b32_e32 v41, v67
	v_lshl_add_u64 v[46:47], v[44:45], 0, v[40:41]
	s_nop 1
	v_cvt_pk_bf16_f32 v2, v2, v3
	v_cvt_pk_bf16_f32 v3, v4, v5
	global_store_dwordx2 v[46:47], v[2:3], off sc1
	v_cvt_pk_bf16_f32 v2, v6, v7
	v_cvt_pk_bf16_f32 v3, v8, v9
	global_store_dwordx2 v[46:47], v[2:3], off offset:16 sc1
	v_cvt_pk_bf16_f32 v2, v10, v11
	v_cvt_pk_bf16_f32 v3, v12, v13
	global_store_dwordx2 v[46:47], v[2:3], off offset:32 sc1
	v_cvt_pk_bf16_f32 v2, v14, v15
	v_cvt_pk_bf16_f32 v3, v16, v17
	v_mov_b32_e32 v43, v67
	global_store_dwordx2 v[46:47], v[2:3], off offset:48 sc1
	v_lshl_add_u64 v[2:3], v[44:45], 0, v[42:43]
	v_cvt_pk_bf16_f32 v4, v18, v19
	v_cvt_pk_bf16_f32 v5, v20, v21
	global_store_dwordx2 v[2:3], v[4:5], off sc1
	v_cvt_pk_bf16_f32 v4, v22, v23
	v_cvt_pk_bf16_f32 v5, v24, v25
	global_store_dwordx2 v[2:3], v[4:5], off offset:16 sc1
	v_cvt_pk_bf16_f32 v4, v26, v27
	v_cvt_pk_bf16_f32 v5, v28, v29
	global_store_dwordx2 v[2:3], v[4:5], off offset:32 sc1
	v_cvt_pk_bf16_f32 v4, v30, v31
	v_cvt_pk_bf16_f32 v5, v32, v33
	global_store_dwordx2 v[2:3], v[4:5], off offset:48 sc1
	s_and_saveexec_b64 s[12:13], s[36:37]
	s_cbranch_execz .LBB0_285
	s_lshl_b64 s[10:11], s[10:11], 9
	v_lshl_add_u64 v[2:3], v[36:37], 0, s[10:11]
	global_store_dword v[2:3], v84, off sc1
	s_branch .LBB0_285

; __device__ __forceinline__ unsigned xb_ld(unsigned* p)              { return __hip_atomic_load(p, __ATOMIC_RELAXED, __HIP_MEMORY_SCOPE_AGENT); }
; __device__ __forceinline__ unsigned xb_add(unsigned* p, unsigned v) { return __hip_atomic_fetch_add(p, v, __ATOMIC_RELAXED, __HIP_MEMORY_SCOPE_AGENT); }
; #define XB_SPIN(cond, bar) do { unsigned _sp = 0; while (cond) { __builtin_amdgcn_s_sleep(1); \
;     if ((++_sp & 255u) == 0u) { if (xb_ld(&(bar)[XB_TMO])) break; if (_sp > XB_SPIN_CAP) { atomicAdd(&(bar)[XB_TMO], 1u); break; } } } } while (0)
; #define SEAM(k) do { if (IN(k) && IN((k) + 1)) xcd_barrier(bar); } while (0)
; __device__ __forceinline__ void xcd_barrier(const XcdBarrier& b) {
;     asm volatile("s_waitcnt vmcnt(0)" ::: "memory");
;     __syncthreads();
;     if (threadIdx.x == 0) {
;         unsigned* bar = b.bar;
;         __builtin_amdgcn_s_waitcnt(0);
;         unsigned nloc = b.st[0], nx = b.st[1];
;         if (nloc == 0u) { xcd_barrier_complete(bar, b.x, nloc, nx); b.st[0] = nloc; b.st[1] = nx; }
;         const unsigned old = xb_add(&bar[XB_XSUB(b.x)], 1u);
;         const unsigned gen = old / nloc;
;         if (old + 1u == (gen + 1u) * nloc) {
;             __builtin_amdgcn_fence(__ATOMIC_RELEASE, "agent");
;             asm volatile("s_waitcnt vmcnt(0)" ::: "memory");
;             const unsigned og = xb_add(&bar[XB_TOP], 1u);
;             const unsigned tg = og / nx;
;             if (og + 1u == (tg + 1u) * nx) xb_add(&bar[XB_TOPGEN], 1u);
;             else XB_SPIN(xb_ld(&bar[XB_TOPGEN]) == tg, bar);
;             __builtin_amdgcn_fence(__ATOMIC_ACQUIRE, "agent");
;             xb_add(&bar[XB_XGEN(b.x)], 1u);
;             asm volatile("s_waitcnt vmcnt(0)" ::: "memory");
;         } else {
;             XB_SPIN(xb_ld(&bar[XB_XGEN(b.x)]) == gen, bar);
;             __builtin_amdgcn_fence(__ATOMIC_ACQUIRE, "agent");
;             asm volatile("s_waitcnt vmcnt(0)" ::: "memory");
;         }
;     }
;     __syncthreads();
; }
; __global__ void __launch_bounds__(NTHR, 2) fwd_kernel(Args args) {
;     ...
;         SEAM(pb + 1);
.LBB0_324:
	v_readlane_b32 s2, v255, 16
	s_add_i32 s2, s2, 4
	s_cmp_lt_i32 s2, s51
	s_cselect_b64 s[8:9], -1, 0
	s_and_b64 s[0:1], s[0:1], s[8:9]
	s_andn2_b64 vcc, exec, s[0:1]
	s_cbranch_vccnz .LBB0_378
	s_waitcnt vmcnt(0)
	s_waitcnt vmcnt(0) lgkmcnt(0)
	s_barrier
	v_readlane_b32 s6, v255, 16
	v_readlane_b32 s7, v253, 36
	s_mov_b32 s10, s70
	v_mov_b32_e32 v2, s6
.Lmy_pub_loop:
	s_cmpk_gt_i32 s10, 0xff
	s_cbranch_scc1 .Lmy_pub_done
	s_lshl_b32 s11, s10, 6
	s_add_u32 s12, s48, s11
	s_addc_u32 s13, s49, 0
	s_add_u32 s12, s12, 0x20000
	s_addc_u32 s13, s13, 0
	s_add_i32 s10, s10, s7
	global_store_dword v67, v2, s[12:13] sc1
	s_branch .Lmy_pub_loop
.Lmy_pub_done:
.LBB0_378:
	s_cmp_le_i32 s50, s2
	s_cselect_b64 s[0:1], -1, 0
	s_and_b64 s[8:9], s[0:1], s[8:9]
	v_readlane_b32 s0, v255, 16
	s_add_i32 s2, s0, 5
	s_cmp_lt_i32 s2, s51
	s_cselect_b64 s[0:1], -1, 0
	s_and_b64 s[6:7], s[8:9], s[0:1]

; __device__ __forceinline__ unsigned pk2(float lo, float hi) { return cvt_pk_bf16(lo, hi); }
; #define M3_LOAD(un) do { const int bh_ = (un) >> 6, c_ = (un) & 63; const bf16* prow_ = PROJ + ((size_t)(bh_ >> 2) * SEQ + 64 * c_ + 16 * i) * NPROJ + 128 * (bh_ & 3) + k; \
;         _Pragma("unroll") for (int j = 0; j < 16; ++j) { qr[j] = prow_[(size_t)j * NPROJ + C_HQ]; gr[j] = prow_[(size_t)j * NPROJ + C_HG]; vq[j] = prow_[(size_t)j * NPROJ + C_HV]; } } while (0)
; __device__ __forceinline__ void hgrn_m2(Frame& F) {
;     ...
;         bf16* p = RS + (size_t)bh * 4 * 16384 + e0; const float* dp = RD + (size_t)bh * 4 * 128 + k0;
; #pragma unroll
;         for (int c = 0; c < 4; ++c) {
;             const u32x4 u = *(const u32x4*)(p + (size_t)c * 16384);
;             const f32x4 d0 = *(const f32x4*)(dp + c * 128), d1 = *(const f32x4*)(dp + c * 128 + 4);
;             u32x4 o; o.x = pk2(S[0], S[1]); o.y = pk2(S[2], S[3]); o.z = pk2(S[4], S[5]); o.w = pk2(S[6], S[7]);
;             *(u32x4*)(p + (size_t)c * 16384) = o;
;             S[0] = d0[0] * S[0] + bflo(u.x); S[1] = d0[1] * S[1] + bfhi(u.x); S[2] = d0[2] * S[2] + bflo(u.y); S[3] = d0[3] * S[3] + bfhi(u.y);
;             S[4] = d1[0] * S[4] + bflo(u.z); S[5] = d1[1] * S[5] + bfhi(u.z); S[6] = d1[2] * S[6] + bflo(u.w); S[7] = d1[3] * S[7] + bfhi(u.w);
; __device__ __forceinline__ void hgrn_m3(Frame& F) {
;     ...
;     if (F.bx < 256) M3_LOAD(16 * F.bx);
;     for (int rg = F.bx; rg < 256; rg += F.G) {
;       f32x16 st[2];
; #pragma unroll
;       for (int x = 0; x < 2; ++x)
; #pragma unroll
;           for (int g4 = 0; g4 < 4; ++g4) { const u32x2 w = *(const u32x2*)(RS + (size_t)rg * 16384 + (size_t)(32 * (vt0 + x) + r32) * 128 + 32 * kt + 8 * g4 + 4 * hi5);
;               st[x][4 * g4] = bflo(w.x); st[x][4 * g4 + 1] = bfhi(w.x); st[x][4 * g4 + 2] = bflo(w.y); st[x][4 * g4 + 3] = bfhi(w.y); }
.LBB0_443:
	s_and_b32 s1, s0, 3
	s_cmp_eq_u32 s1, 0
	s_cbranch_scc1 .Lmy_fl_done
	v_readlane_b32 s7, v255, 19
	v_readlane_b32 s16, v255, 20
	v_readlane_b32 s12, v255, 16
	s_mov_b32 s13, s1
.Lmy_fl_next:
	s_sub_i32 s24, s0, s13
	s_lshl_b32 s24, s24, 6
	s_add_u32 s24, s7, s24
	s_addc_u32 s25, s16, 0
	s_add_u32 s24, s24, 0x20000
	s_addc_u32 s25, s25, 0
	s_mov_b32 vcc_lo, 0
.Lmy_fl_poll:
	global_load_dword v71, v67, s[24:25] sc1
	s_waitcnt vmcnt(0)
	v_readfirstlane_b32 s26, v71
	s_cmp_ge_u32 s26, s12
	s_cbranch_scc1 .Lmy_fl_got
	s_sleep 2
	s_add_i32 vcc_lo, vcc_lo, 1
	s_cmp_lt_u32 vcc_lo, 0x400000
	s_cbranch_scc1 .Lmy_fl_poll
.Lmy_fl_got:
	s_sub_i32 s13, s13, 1
	s_cmp_lg_u32 s13, 0
	s_cbranch_scc1 .Lmy_fl_next
.Lmy_fl_done:
	s_sub_i32 s24, s0, s1
	s_lshl_b32 s12, s24, 9
	s_lshl_b32 s24, s24, 15
	v_readlane_b32 s7, v255, 19
	v_readlane_b32 s16, v255, 20
	s_add_u32 s24, s7, s24
	s_addc_u32 s25, s16, 0
	s_add_u32 s24, s24, 0x4900000
	s_addc_u32 s25, s25, 0
	s_add_u32 s12, s7, s12
	s_addc_u32 s13, s16, 0
	s_add_u32 s12, s12, 0x5100000
	s_addc_u32 s13, s13, 0
	v_and_b32_e32 v68, 31, v0
	v_lshlrev_b32_e32 v68, 8, v68
	v_bfe_u32 v69, v0, 6, 1
	v_lshl_add_u32 v68, v69, 14, v68
	v_lshl_add_u32 v68, v72, 6, v68
	v_bfe_u32 v69, v0, 5, 1
	v_lshl_add_u32 v68, v69, 3, v68
	v_add_u32_e32 v70, 0x2000, v68
	v_lshlrev_b32_e32 v69, 4, v69
	v_lshl_add_u32 v69, v72, 7, v69
	s_cmp_eq_u32 s1, 0
	s_cbranch_scc1 .Lmy_m3_s0
	global_load_dwordx2 v[34:35], v68, s[24:25] sc1
	global_load_dwordx2 v[36:37], v68, s[24:25] offset:16 sc1
	global_load_dwordx2 v[38:39], v68, s[24:25] offset:32 sc1
	global_load_dwordx2 v[40:41], v68, s[24:25] offset:48 sc1
	global_load_dwordx2 v[42:43], v70, s[24:25] sc1
	global_load_dwordx2 v[44:45], v70, s[24:25] offset:16 sc1
	global_load_dwordx2 v[46:47], v70, s[24:25] offset:32 sc1
	global_load_dwordx2 v[48:49], v70, s[24:25] offset:48 sc1
	s_waitcnt vmcnt(0)
	v_lshlrev_b32_e32 v2, 16, v34
	v_and_b32_e32 v3, 0xffff0000, v34
	v_lshlrev_b32_e32 v4, 16, v35
	v_and_b32_e32 v5, 0xffff0000, v35
	v_lshlrev_b32_e32 v6, 16, v36
	v_and_b32_e32 v7, 0xffff0000, v36
	v_lshlrev_b32_e32 v8, 16, v37
	v_and_b32_e32 v9, 0xffff0000, v37
	v_lshlrev_b32_e32 v10, 16, v38
	v_and_b32_e32 v11, 0xffff0000, v38
	v_lshlrev_b32_e32 v12, 16, v39
	v_and_b32_e32 v13, 0xffff0000, v39
	v_lshlrev_b32_e32 v14, 16, v40
	v_and_b32_e32 v15, 0xffff0000, v40
	v_lshlrev_b32_e32 v16, 16, v41
	v_and_b32_e32 v17, 0xffff0000, v41
	v_lshlrev_b32_e32 v18, 16, v42
	v_and_b32_e32 v19, 0xffff0000, v42
	v_lshlrev_b32_e32 v20, 16, v43
	v_and_b32_e32 v21, 0xffff0000, v43
	v_lshlrev_b32_e32 v22, 16, v44
	v_and_b32_e32 v23, 0xffff0000, v44
	v_lshlrev_b32_e32 v24, 16, v45
	v_and_b32_e32 v25, 0xffff0000, v45
	v_lshlrev_b32_e32 v26, 16, v46
	v_and_b32_e32 v27, 0xffff0000, v46
	v_lshlrev_b32_e32 v28, 16, v47
	v_and_b32_e32 v29, 0xffff0000, v47
	v_lshlrev_b32_e32 v30, 16, v48
	v_and_b32_e32 v31, 0xffff0000, v48
	v_lshlrev_b32_e32 v32, 16, v49
	v_and_b32_e32 v33, 0xffff0000, v49
	v_add_f32_e32 v2, 0, v2
	v_add_f32_e32 v3, 0, v3
	v_add_f32_e32 v4, 0, v4
	v_add_f32_e32 v5, 0, v5
	v_add_f32_e32 v6, 0, v6
	v_add_f32_e32 v7, 0, v7
	v_add_f32_e32 v8, 0, v8
	v_add_f32_e32 v9, 0, v9
	v_add_f32_e32 v10, 0, v10
	v_add_f32_e32 v11, 0, v11
	v_add_f32_e32 v12, 0, v12
	v_add_f32_e32 v13, 0, v13
	v_add_f32_e32 v14, 0, v14
	v_add_f32_e32 v15, 0, v15
	v_add_f32_e32 v16, 0, v16
	v_add_f32_e32 v17, 0, v17
	v_add_f32_e32 v18, 0, v18
	v_add_f32_e32 v19, 0, v19
	v_add_f32_e32 v20, 0, v20
	v_add_f32_e32 v21, 0, v21
	v_add_f32_e32 v22, 0, v22
	v_add_f32_e32 v23, 0, v23
	v_add_f32_e32 v24, 0, v24
	v_add_f32_e32 v25, 0, v25
	v_add_f32_e32 v26, 0, v26
	v_add_f32_e32 v27, 0, v27
	v_add_f32_e32 v28, 0, v28
	v_add_f32_e32 v29, 0, v29
	v_add_f32_e32 v30, 0, v30
	v_add_f32_e32 v31, 0, v31
	v_add_f32_e32 v32, 0, v32
	v_add_f32_e32 v33, 0, v33
	s_cmp_eq_u32 s1, 1
	s_cbranch_scc1 .Lmy_m3_round
; __device__ __forceinline__ unsigned pk2(float lo, float hi) { return cvt_pk_bf16(lo, hi); }
; __device__ __forceinline__ void hgrn_m2(Frame& F) {
;     ...
;         bf16* p = RS + (size_t)bh * 4 * 16384 + e0; const float* dp = RD + (size_t)bh * 4 * 128 + k0;
; #pragma unroll
;         for (int c = 0; c < 4; ++c) {
;             const u32x4 u = *(const u32x4*)(p + (size_t)c * 16384);
;             const f32x4 d0 = *(const f32x4*)(dp + c * 128), d1 = *(const f32x4*)(dp + c * 128 + 4);
;             u32x4 o; o.x = pk2(S[0], S[1]); o.y = pk2(S[2], S[3]); o.z = pk2(S[4], S[5]); o.w = pk2(S[6], S[7]);
;             *(u32x4*)(p + (size_t)c * 16384) = o;
;             S[0] = d0[0] * S[0] + bflo(u.x); S[1] = d0[1] * S[1] + bfhi(u.x); S[2] = d0[2] * S[2] + bflo(u.y); S[3] = d0[3] * S[3] + bfhi(u.y);
;             S[4] = d1[0] * S[4] + bflo(u.z); S[5] = d1[1] * S[5] + bfhi(u.z); S[6] = d1[2] * S[6] + bflo(u.w); S[7] = d1[3] * S[7] + bfhi(u.w);
;         }
	s_add_u32 s24, s24, 0x8000
	s_addc_u32 s25, s25, 0
	s_add_u32 s12, s12, 0x200
	s_addc_u32 s13, s13, 0
	global_load_dwordx2 v[34:35], v68, s[24:25] sc1
	global_load_dwordx2 v[36:37], v68, s[24:25] offset:16 sc1
	global_load_dwordx2 v[38:39], v68, s[24:25] offset:32 sc1
	global_load_dwordx2 v[40:41], v68, s[24:25] offset:48 sc1
	global_load_dwordx2 v[42:43], v70, s[24:25] sc1
	global_load_dwordx2 v[44:45], v70, s[24:25] offset:16 sc1
	global_load_dwordx2 v[46:47], v70, s[24:25] offset:32 sc1
	global_load_dwordx2 v[48:49], v70, s[24:25] offset:48 sc1
	global_load_dwordx4 v[50:53], v69, s[12:13] sc1
	global_load_dwordx4 v[54:57], v69, s[12:13] offset:32 sc1
	global_load_dwordx4 v[58:61], v69, s[12:13] offset:64 sc1
	global_load_dwordx4 v[62:65], v69, s[12:13] offset:96 sc1
	s_waitcnt vmcnt(0)
	v_lshlrev_b32_e32 v71, 16, v34
	v_fma_f32 v2, v2, v50, v71
	v_and_b32_e32 v71, 0xffff0000, v34
	v_fma_f32 v3, v3, v51, v71
	v_lshlrev_b32_e32 v71, 16, v35
	v_fma_f32 v4, v4, v52, v71
	v_and_b32_e32 v71, 0xffff0000, v35
	v_fma_f32 v5, v5, v53, v71
	v_lshlrev_b32_e32 v71, 16, v36
	v_fma_f32 v6, v6, v54, v71
	v_and_b32_e32 v71, 0xffff0000, v36
	v_fma_f32 v7, v7, v55, v71
	v_lshlrev_b32_e32 v71, 16, v37
	v_fma_f32 v8, v8, v56, v71
	v_and_b32_e32 v71, 0xffff0000, v37
	v_fma_f32 v9, v9, v57, v71
	v_lshlrev_b32_e32 v71, 16, v38
	v_fma_f32 v10, v10, v58, v71
	v_and_b32_e32 v71, 0xffff0000, v38
	v_fma_f32 v11, v11, v59, v71
	v_lshlrev_b32_e32 v71, 16, v39
	v_fma_f32 v12, v12, v60, v71
	v_and_b32_e32 v71, 0xffff0000, v39
	v_fma_f32 v13, v13, v61, v71
	v_lshlrev_b32_e32 v71, 16, v40
	v_fma_f32 v14, v14, v62, v71
	v_and_b32_e32 v71, 0xffff0000, v40
	v_fma_f32 v15, v15, v63, v71
	v_lshlrev_b32_e32 v71, 16, v41
	v_fma_f32 v16, v16, v64, v71
	v_and_b32_e32 v71, 0xffff0000, v41
	v_fma_f32 v17, v17, v65, v71
	v_lshlrev_b32_e32 v71, 16, v42
	v_fma_f32 v18, v18, v50, v71
	v_and_b32_e32 v71, 0xffff0000, v42
	v_fma_f32 v19, v19, v51, v71
	v_lshlrev_b32_e32 v71, 16, v43
	v_fma_f32 v20, v20, v52, v71
	v_and_b32_e32 v71, 0xffff0000, v43
	v_fma_f32 v21, v21, v53, v71
	v_lshlrev_b32_e32 v71, 16, v44
	v_fma_f32 v22, v22, v54, v71
	v_and_b32_e32 v71, 0xffff0000, v44
	v_fma_f32 v23, v23, v55, v71
	v_lshlrev_b32_e32 v71, 16, v45
	v_fma_f32 v24, v24, v56, v71
	v_and_b32_e32 v71, 0xffff0000, v45
	v_fma_f32 v25, v25, v57, v71
	v_lshlrev_b32_e32 v71, 16, v46
	v_fma_f32 v26, v26, v58, v71
	v_and_b32_e32 v71, 0xffff0000, v46
	v_fma_f32 v27, v27, v59, v71
	v_lshlrev_b32_e32 v71, 16, v47
	v_fma_f32 v28, v28, v60, v71
	v_and_b32_e32 v71, 0xffff0000, v47
	v_fma_f32 v29, v29, v61, v71
	v_lshlrev_b32_e32 v71, 16, v48
	v_fma_f32 v30, v30, v62, v71
	v_and_b32_e32 v71, 0xffff0000, v48
	v_fma_f32 v31, v31, v63, v71
	v_lshlrev_b32_e32 v71, 16, v49
	v_fma_f32 v32, v32, v64, v71
	v_and_b32_e32 v71, 0xffff0000, v49
	v_fma_f32 v33, v33, v65, v71
	s_cmp_eq_u32 s1, 2
	s_cbranch_scc1 .Lmy_m3_round
	s_add_u32 s24, s24, 0x8000
	s_addc_u32 s25, s25, 0
	s_add_u32 s12, s12, 0x200
	s_addc_u32 s13, s13, 0
	global_load_dwordx2 v[34:35], v68, s[24:25] sc1
	global_load_dwordx2 v[36:37], v68, s[24:25] offset:16 sc1
	global_load_dwordx2 v[38:39], v68, s[24:25] offset:32 sc1
	global_load_dwordx2 v[40:41], v68, s[24:25] offset:48 sc1
	global_load_dwordx2 v[42:43], v70, s[24:25] sc1
	global_load_dwordx2 v[44:45], v70, s[24:25] offset:16 sc1
	global_load_dwordx2 v[46:47], v70, s[24:25] offset:32 sc1
	global_load_dwordx2 v[48:49], v70, s[24:25] offset:48 sc1
	global_load_dwordx4 v[50:53], v69, s[12:13] sc1
	global_load_dwordx4 v[54:57], v69, s[12:13] offset:32 sc1
	global_load_dwordx4 v[58:61], v69, s[12:13] offset:64 sc1
	global_load_dwordx4 v[62:65], v69, s[12:13] offset:96 sc1
	s_waitcnt vmcnt(0)
	v_lshlrev_b32_e32 v71, 16, v34
	v_fma_f32 v2, v2, v50, v71
	v_and_b32_e32 v71, 0xffff0000, v34
	v_fma_f32 v3, v3, v51, v71
	v_lshlrev_b32_e32 v71, 16, v35
	v_fma_f32 v4, v4, v52, v71
	v_and_b32_e32 v71, 0xffff0000, v35
	v_fma_f32 v5, v5, v53, v71
	v_lshlrev_b32_e32 v71, 16, v36
	v_fma_f32 v6, v6, v54, v71
	v_and_b32_e32 v71, 0xffff0000, v36
	v_fma_f32 v7, v7, v55, v71
	v_lshlrev_b32_e32 v71, 16, v37
	v_fma_f32 v8, v8, v56, v71
	v_and_b32_e32 v71, 0xffff0000, v37
	v_fma_f32 v9, v9, v57, v71
	v_lshlrev_b32_e32 v71, 16, v38
	v_fma_f32 v10, v10, v58, v71
	v_and_b32_e32 v71, 0xffff0000, v38
	v_fma_f32 v11, v11, v59, v71
	v_lshlrev_b32_e32 v71, 16, v39
	v_fma_f32 v12, v12, v60, v71
	v_and_b32_e32 v71, 0xffff0000, v39
	v_fma_f32 v13, v13, v61, v71
	v_lshlrev_b32_e32 v71, 16, v40
	v_fma_f32 v14, v14, v62, v71
	v_and_b32_e32 v71, 0xffff0000, v40
	v_fma_f32 v15, v15, v63, v71
	v_lshlrev_b32_e32 v71, 16, v41
	v_fma_f32 v16, v16, v64, v71
	v_and_b32_e32 v71, 0xffff0000, v41
	v_fma_f32 v17, v17, v65, v71
	v_lshlrev_b32_e32 v71, 16, v42
	v_fma_f32 v18, v18, v50, v71
	v_and_b32_e32 v71, 0xffff0000, v42
	v_fma_f32 v19, v19, v51, v71
	v_lshlrev_b32_e32 v71, 16, v43
	v_fma_f32 v20, v20, v52, v71
	v_and_b32_e32 v71, 0xffff0000, v43
	v_fma_f32 v21, v21, v53, v71
	v_lshlrev_b32_e32 v71, 16, v44
	v_fma_f32 v22, v22, v54, v71
	v_and_b32_e32 v71, 0xffff0000, v44
	v_fma_f32 v23, v23, v55, v71
	v_lshlrev_b32_e32 v71, 16, v45
	v_fma_f32 v24, v24, v56, v71
	v_and_b32_e32 v71, 0xffff0000, v45
	v_fma_f32 v25, v25, v57, v71
	v_lshlrev_b32_e32 v71, 16, v46
	v_fma_f32 v26, v26, v58, v71
	v_and_b32_e32 v71, 0xffff0000, v46
	v_fma_f32 v27, v27, v59, v71
	v_lshlrev_b32_e32 v71, 16, v47
	v_fma_f32 v28, v28, v60, v71
	v_and_b32_e32 v71, 0xffff0000, v47
	v_fma_f32 v29, v29, v61, v71
	v_lshlrev_b32_e32 v71, 16, v48
	v_fma_f32 v30, v30, v62, v71
	v_and_b32_e32 v71, 0xffff0000, v48
	v_fma_f32 v31, v31, v63, v71
	v_lshlrev_b32_e32 v71, 16, v49
	v_fma_f32 v32, v32, v64, v71
	v_and_b32_e32 v71, 0xffff0000, v49
	v_fma_f32 v33, v33, v65, v71
